# speedup vs baseline: 1.0112x; 1.0112x over previous
; __device__ __forceinline__ int sub_op() { return __builtin_amdgcn_readfirstlane((int)(threadIdx.x >> 8)); }
; #define LAS __attribute__((address_space(3)))
; __global__ void __launch_bounds__(512, 2) mega_kernel(Params p) {
;   __shared__ __attribute__((aligned(16))) char smem[2 * SMEM_BYTES + 16];
;   __shared__ uint4 xb_words;
;   if (threadIdx.x == 0) xb_words = make_uint4(0u, 0u, 0u, 0u);
;   __syncthreads();
;   const XcdBarrier xb = xcd_barrier_post(p.bar, (volatile LAS unsigned*)&xb_words, (unsigned)(p.nblk >> 1));
;   run_range<0, NPHASE>(p, smem + sub_op() * SMEM_BYTES, smem, xb);
_Z11mega_kernel6Params:
	s_load_dwordx4 s[4:7], s[0:1], 0x140
	v_readfirstlane_b32 vcc_lo, v0
	s_bfe_u32 vcc_lo, vcc_lo, 0x20008
	s_cmp_eq_u32 vcc_lo, 0
	s_cbranch_scc1 .Lprio_skip
	s_setprio 1
.Lprio_skip:
	v_and_b32_e32 v252, 0x3ff, v0
	v_writelane_b32 v253, s2, 0
	s_waitcnt lgkmcnt(0)
	v_writelane_b32 v253, s4, 1
	s_nop 1
	v_writelane_b32 v253, s5, 2
	v_writelane_b32 v253, s6, 3
	v_writelane_b32 v253, s7, 4
	v_cmp_eq_u32_e64 s[4:5], 0, v252
	s_mov_b64 s[2:3], exec
	s_nop 0
	v_writelane_b32 v253, s4, 5
	s_nop 1
	v_writelane_b32 v253, s5, 6
	s_and_b64 s[4:5], s[2:3], s[4:5]
	s_mov_b64 exec, s[4:5]
	s_cbranch_execz .LBB0_2
	v_mov_b32_e32 v2, 0
	v_mov_b32_e32 v3, v2
	v_mov_b32_e32 v4, v2
	v_mov_b32_e32 v5, v2
	v_mov_b32_e32 v1, 0x26010
	ds_write_b128 v1, v[2:5]
